# speedup vs baseline: 1.0038x; 1.0000x over previous
; #define LAS __attribute__((address_space(3)))
; __global__ void __launch_bounds__(512) mega(P p) {
;     extern __shared__ __attribute__((aligned(16))) unsigned char smem[];
;     LAS unsigned char* lds = (LAS unsigned char*)smem;
;     cg::grid_group grid = cg::this_grid();
;     unsigned* bar = (unsigned*)(p.ws + O_BAR);
;     volatile LAS unsigned* st = (volatile LAS unsigned*)(lds + LDS_BYTES - 16);
;     if (threadIdx.x < 4) st[threadIdx.x] = 0u;
;     __syncthreads();
;     if (p.ph0 > p.ph1) grid.sync();
;     const XcdBarrier xb = xcd_barrier_post(bar, st);
_Z4mega1P:
	s_add_u32 s4, s0, 0x138
	v_writelane_b32 v250, s2, 0
	s_load_dwordx2 s[14:15], s[0:1], 0x108
	s_load_dwordx2 s[2:3], s[0:1], 0x138
	v_and_b32_e32 v198, 0x3ff, v0
	v_cmp_gt_u32_e32 vcc, 4, v198
	s_waitcnt lgkmcnt(0)
	v_writelane_b32 v250, s2, 1
	s_nop 1
	v_writelane_b32 v250, s3, 2
	v_writelane_b32 v250, s0, 3
	s_addc_u32 s5, s1, 0
	s_nop 0
	v_writelane_b32 v250, s1, 4
	s_and_saveexec_b64 s[2:3], vcc
	v_lshl_add_u32 v1, v198, 2, 0
	v_add_u32_e32 v1, 0x21ff0, v1
	v_mov_b32_e32 v2, 0
	ds_write_b32 v1, v2
	s_or_b64 exec, exec, s[2:3]
	v_readlane_b32 s0, v250, 3
	v_readlane_b32 s1, v250, 4
	s_load_dwordx2 s[0:1], s[0:1], 0x130
	s_waitcnt lgkmcnt(0)
	s_barrier
	s_cmp_le_i32 s0, s1
	s_cbranch_scc1 .LBB0_14
	v_lshrrev_b32_e32 v1, 20, v0
	v_lshrrev_b32_e32 v0, 10, v0
	v_or_b32_e32 v0, v0, v1
	s_movk_i32 s2, 0x3ff
	v_and_or_b32 v0, v0, s2, v198
	v_cmp_eq_u32_e32 vcc, 0, v0
	s_barrier
	s_and_saveexec_b64 s[2:3], vcc
	s_cbranch_execz .LBB0_13
	buffer_wbl2 sc1
	s_load_dwordx2 s[4:5], s[4:5], 0x58
	s_mov_b64 s[6:7], exec
	v_mbcnt_lo_u32_b32 v0, s6, 0
	v_mbcnt_hi_u32_b32 v0, s7, v0
	v_cmp_eq_u32_e32 vcc, 0, v0
	s_waitcnt lgkmcnt(0)
	s_load_dword s10, s[4:5], 0x28
	s_and_saveexec_b64 s[8:9], vcc
	s_cbranch_execz .LBB0_6
	s_bcnt1_i32_b64 s6, s[6:7]
	v_mov_b32_e32 v1, 0
	v_mov_b32_e32 v2, s6
	global_atomic_add v1, v1, v2, s[4:5] offset:32 sc0

; __global__ void __launch_bounds__(512) mega(P p) {
;     ...
;     for (int ph = p.ph0; ph < p.ph1; ++ph) {
;         run_phase(p, ph, lds);
;         if (ph + 1 < p.ph1) xcd_barrier(xb);
;     }
.LBB0_786:
	v_readlane_b32 s0, v250, 3
	v_readlane_b32 s1, v250, 4
	s_load_dword s0, s[0:1], 0x134
	v_readlane_b32 s4, v250, 7
	v_readlane_b32 s5, v250, 8
	s_add_i32 s4, s4, 1
	v_writelane_b32 v250, s4, 7
	s_waitcnt lgkmcnt(0)
	s_cmp_ge_i32 s4, s0
	v_writelane_b32 v250, s5, 8
	s_cbranch_scc0 .LBB0_787
	s_getpc_b64 s[98:99]

; #define LAS __attribute__((address_space(3)))
; __global__ void __launch_bounds__(512) mega(P p) {
;     extern __shared__ __attribute__((aligned(16))) unsigned char smem[];
;     LAS unsigned char* lds = (LAS unsigned char*)smem;
;     cg::grid_group grid = cg::this_grid();
;     unsigned* bar = (unsigned*)(p.ws + O_BAR);
;     volatile LAS unsigned* st = (volatile LAS unsigned*)(lds + LDS_BYTES - 16);
;     if (threadIdx.x < 4) st[threadIdx.x] = 0u;
;     __syncthreads();
;     if (p.ph0 > p.ph1) grid.sync();
;     const XcdBarrier xb = xcd_barrier_post(bar, st);
;     for (int ph = p.ph0; ph < p.ph1; ++ph) {
;         run_phase(p, ph, lds);
;         if (ph + 1 < p.ph1) xcd_barrier(xb);
;     }
; }
	.amdhsa_kernel _Z4mega1P
		.amdhsa_group_segment_fixed_size 0
		.amdhsa_private_segment_fixed_size 0
		.amdhsa_kernarg_size 568
		.amdhsa_user_sgpr_count 2
		.amdhsa_user_sgpr_dispatch_ptr 0
		.amdhsa_user_sgpr_queue_ptr 0
		.amdhsa_user_sgpr_kernarg_segment_ptr 1
		.amdhsa_user_sgpr_dispatch_id 0
		.amdhsa_user_sgpr_kernarg_preload_length 0
		.amdhsa_user_sgpr_kernarg_preload_offset 0
		.amdhsa_user_sgpr_private_segment_size 0
		.amdhsa_uses_dynamic_stack 0
		.amdhsa_enable_private_segment 0
		.amdhsa_system_sgpr_workgroup_id_x 1
		.amdhsa_system_sgpr_workgroup_id_y 0
		.amdhsa_system_sgpr_workgroup_id_z 0
		.amdhsa_system_sgpr_workgroup_info 0
		.amdhsa_system_vgpr_workitem_id 2
		.amdhsa_next_free_vgpr 256
		.amdhsa_next_free_sgpr 100
		.amdhsa_accum_offset 256
		.amdhsa_reserve_vcc 1
		.amdhsa_float_round_mode_32 0
		.amdhsa_float_round_mode_16_64 0
		.amdhsa_float_denorm_mode_32 3
		.amdhsa_float_denorm_mode_16_64 3
		.amdhsa_dx10_clamp 1
		.amdhsa_ieee_mode 1
		.amdhsa_fp16_overflow 0
		.amdhsa_tg_split 0
		.amdhsa_exception_fp_ieee_invalid_op 0
		.amdhsa_exception_fp_denorm_src 0
		.amdhsa_exception_fp_ieee_div_zero 0
		.amdhsa_exception_fp_ieee_overflow 0
		.amdhsa_exception_fp_ieee_underflow 0
		.amdhsa_exception_fp_ieee_inexact 0
		.amdhsa_exception_int_div_zero 0
	.end_amdhsa_kernel

amdhsa.kernels:
  - .agpr_count:     0
    .args:
      - .offset:         0
        .size:           312
        .value_kind:     by_value
      - .offset:         312
        .size:           4
        .value_kind:     hidden_block_count_x
      - .offset:         316
        .size:           4
        .value_kind:     hidden_block_count_y
      - .offset:         320
        .size:           4
        .value_kind:     hidden_block_count_z
      - .offset:         324
        .size:           2
        .value_kind:     hidden_group_size_x
      - .offset:         326
        .size:           2
        .value_kind:     hidden_group_size_y
      - .offset:         328
        .size:           2
        .value_kind:     hidden_group_size_z
      - .offset:         330
        .size:           2
        .value_kind:     hidden_remainder_x
      - .offset:         332
        .size:           2
        .value_kind:     hidden_remainder_y
      - .offset:         334
        .size:           2
        .value_kind:     hidden_remainder_z
      - .offset:         352
        .size:           8
        .value_kind:     hidden_global_offset_x
      - .offset:         360
        .size:           8
        .value_kind:     hidden_global_offset_y
      - .offset:         368
        .size:           8
        .value_kind:     hidden_global_offset_z
      - .offset:         376
        .size:           2
        .value_kind:     hidden_grid_dims
      - .offset:         400
        .size:           8
        .value_kind:     hidden_multigrid_sync_arg
      - .offset:         432
        .size:           4
        .value_kind:     hidden_dynamic_lds_size
    .group_segment_fixed_size: 0
    .kernarg_segment_align: 8
    .kernarg_segment_size: 568
    .language:       OpenCL C
    .language_version:
      - 2
      - 0
    .max_flat_workgroup_size: 512
    .name:           _Z4mega1P
    .private_segment_fixed_size: 0
    .sgpr_count:     106
    .sgpr_spill_count: 410
    .symbol:         _Z4mega1P.kd
    .uniform_work_group_size: 1
    .uses_dynamic_stack: false
    .vgpr_count:     256
    .vgpr_spill_count: 0
    .wavefront_size: 64
